# P9 SwiGLU epilogue: per-row ss values prefetched at unit-loop top into free VGPRs instead of loaded+waited at epilogue start
# speedup vs baseline: 1.0087x; 1.0013x over previous
;     __host__ __device__ bool next(int i, Unit& u) const { const bool ok = StaticOrder::next(i >> 1, u); u.z = i & 1; return ok; }
;     __host__ __device__ bool next(int i, Unit& u) const {
;         const long L = (long)i * G + c; if (L >= nwg) return false;
;         int wgid = (int)L; { const int q = nwg / NXCD, r = nwg % NXCD, xcd = wgid % NXCD, off = wgid / NXCD; wgid = (xcd < r ? xcd * (q + 1) : r * (q + 1) + (xcd - r) * q) + off; }
;         const int nig = WGM * nN, gid = wgid / nig, fm = gid * WGM, gsz = (nM - fm) < WGM ? (nM - fm) : WGM;
;         u.pm = fm + ((wgid % nig) % gsz); u.pn = (wgid % nig) / gsz; u.z = 0; return true;
;     __device__ __forceinline__ void operator()(const f32x4 (&acc)[2][2][4][2], const Unit& u, int wr, int wc, int fr, int fq) const {
;     ...
;         for (int ai = 0; ai < 2; ++ai)
; #pragma unroll
;             for (int m = 0; m < 4; ++m) sq[ai][m] = ss[u.pm * BM + ai * HALF + wr * 64 + m * 16 + fr];
.LBB0_1807:
	s_load_dword s23, s[56:57], 0xe0
	v_lshl_add_u32 v233, s2, 8, v166
	v_lshlrev_b32_e32 v233, 2, v233
	global_load_dword v234, v233, s[16:17]
	global_load_dword v235, v233, s[16:17] offset:64
	global_load_dword v236, v233, s[16:17] offset:128
	global_load_dword v237, v233, s[16:17] offset:192
	global_load_dword v238, v233, s[16:17] offset:512
	global_load_dword v239, v233, s[16:17] offset:576
	global_load_dword v240, v233, s[16:17] offset:640
	global_load_dword v241, v233, s[16:17] offset:704
	s_add_i32 s44, s44, 1
	s_mul_i32 s0, s44, s47
	s_waitcnt lgkmcnt(0)
	s_mul_hi_u32 s1, s44, s23
	s_add_i32 s1, s1, s0
	s_mul_i32 s0, s44, s23
	s_add_u32 s26, s0, s74
	s_addc_u32 s27, s1, s38
	v_cmp_gt_i64_e32 vcc, s[26:27], v[146:147]
	v_cmp_lt_i64_e64 s[0:1], s[26:27], v[144:145]
	s_cbranch_vccnz .LBB0_1809
	s_ashr_i32 s22, s26, 31
	s_lshr_b32 s22, s22, 29
	s_add_i32 s22, s26, s22
	s_ashr_i32 s23, s22, 3
	s_and_b32 s22, s22, -8
	s_sub_i32 s22, s26, s22
	s_cmp_lt_i32 s22, 0
	s_cselect_b32 s24, s39, 0x2b0
	s_mul_i32 s22, s22, s24
	s_add_i32 s22, s22, s23
	s_mul_hi_i32 s23, s22, 0x2fa0be83
	s_lshr_b32 s24, s23, 31
	s_ashr_i32 s23, s23, 7
	s_add_i32 s23, s23, s24
	s_lshl_b32 s24, s23, 3
	s_sub_i32 s25, 64, s24
	s_min_i32 s25, s25, 8
	s_abs_i32 s26, s25
	v_cvt_f32_u32_e32 v2, s26
	s_sub_i32 s28, 0, s26
	s_mulk_i32 s23, 0x2b0
	s_sub_i32 s23, s22, s23
	v_rcp_iflag_f32_e32 v2, v2
	s_abs_i32 s22, s23
	s_xor_b32 s27, s23, s25
	s_ashr_i32 s27, s27, 31
	v_mul_f32_e32 v2, 0x4f7ffffe, v2
	v_cvt_u32_f32_e32 v2, v2
	s_nop 0
	v_readfirstlane_b32 s29, v2
	s_mul_i32 s28, s28, s29
	s_mul_hi_u32 s28, s29, s28
	s_add_i32 s29, s29, s28
	s_mul_hi_u32 s28, s22, s29
	s_mul_i32 s29, s28, s26
	s_sub_i32 s22, s22, s29
	s_add_i32 s34, s28, 1
	s_sub_i32 s29, s22, s26
	s_cmp_ge_u32 s22, s26
	s_cselect_b32 s28, s34, s28
	s_cselect_b32 s22, s29, s22
	s_add_i32 s29, s28, 1
	s_cmp_ge_u32 s22, s26
	s_cselect_b32 s22, s29, s28
	s_xor_b32 s22, s22, s27
	s_sub_i32 s22, s22, s27
	s_mul_i32 s25, s22, s25
	s_sub_i32 s23, s23, s25
	s_add_i32 s24, s24, s23

; __device__ __forceinline__ u32x4 pack8f(f32x4 a, f32x4 b) { u32x4 w; w.x = cvtpk(a[0], a[1]); w.y = cvtpk(a[2], a[3]); w.z = cvtpk(b[0], b[1]); w.w = cvtpk(b[2], b[3]); return w; }
; __device__ __forceinline__ f32x4 sig4(f32x4 v) { return (f32x4){sigmoidf_(v[0]), sigmoidf_(v[1]), sigmoidf_(v[2]), sigmoidf_(v[3])}; }
;     __device__ __forceinline__ void operator()(const f32x4 (&acc)[2][2][4][2], const Unit& u, int wr, int wc, int fr, int fq) const {
;         bf16_t* base = act + u.pn * HALF + wc * 32 + 8 * fq;
;         float sq[2][4];
; #pragma unroll
;         for (int ai = 0; ai < 2; ++ai)
; #pragma unroll
;             for (int m = 0; m < 4; ++m) sq[ai][m] = ss[u.pm * BM + ai * HALF + wr * 64 + m * 16 + fr];
;         asm volatile("" ::: "memory");
;         EPI_ROWS_BEGIN
;             const float r = 1.0f / sqrtf(sq[ai][m] * (1.f / 4096.f) + EPS);
;             const f32x4 g0 = acc[ai][0][m][0] * r, g1 = acc[ai][0][m][1] * r;
;             *(u32x4*)(base + row * DFF) = pack8f(g0 * sig4(g0) * (acc[ai][1][m][0] * r), g1 * sig4(g1) * (acc[ai][1][m][1] * r));
.LBB0_1813:
	v_lshl_add_u32 v164, s2, 8, v166
	v_ashrrev_i32_e32 v165, 31, v164
	v_lshl_add_u64 v[148:149], v[164:165], 2, s[16:17]
	v_mov_b32_e32 v165, v234
	v_or_b32_e32 v162, 16, v164
	v_ashrrev_i32_e32 v163, 31, v162
	v_lshl_add_u64 v[148:149], v[162:163], 2, s[16:17]
	v_mov_b32_e32 v163, v235
	v_or_b32_e32 v160, 32, v164
	s_lshl_b32 s2, s3, 7
	v_or_b32_e32 v158, 48, v164
	v_add_u32_e32 v156, 0x80, v164
	v_add_u32_e32 v154, 0x90, v164
	v_add_u32_e32 v152, 0xa0, v164
	v_add_u32_e32 v148, 0xb0, v164
	v_ashrrev_i32_e32 v161, 31, v160
	s_ashr_i32 s3, s2, 31
	v_ashrrev_i32_e32 v159, 31, v158
	v_ashrrev_i32_e32 v157, 31, v156
	v_ashrrev_i32_e32 v155, 31, v154
	v_ashrrev_i32_e32 v153, 31, v152
	v_ashrrev_i32_e32 v149, 31, v148
	v_lshl_add_u64 v[174:175], v[160:161], 2, s[16:17]
	v_lshl_add_u64 v[150:151], s[2:3], 1, v[138:139]
	v_lshl_add_u64 v[176:177], v[158:159], 2, s[16:17]
	v_lshl_add_u64 v[178:179], v[156:157], 2, s[16:17]
	v_lshl_add_u64 v[180:181], v[154:155], 2, s[16:17]
	v_lshl_add_u64 v[182:183], v[152:153], 2, s[16:17]
	v_lshl_add_u64 v[184:185], v[148:149], 2, s[16:17]
	v_mov_b32_e32 v159, v236
	v_mov_b32_e32 v161, v237
	v_mov_b32_e32 v157, v238
	v_mov_b32_e32 v155, v239
	v_mov_b32_e32 v153, v240
	v_mov_b32_e32 v149, v241
	v_readlane_b32 s56, v254, 13
	v_readlane_b32 s57, v254, 14
	s_mov_b32 s54, s78
	s_waitcnt vmcnt(0)
	v_fmamk_f32 v165, v165, 0x39800000, v171
	v_mul_f32_e32 v173, 0x4f800000, v165
	v_cmp_gt_f32_e32 vcc, s50, v165
	v_fmamk_f32 v163, v163, 0x39800000, v171
	s_nop 0
	v_cndmask_b32_e32 v165, v165, v173, vcc
	v_sqrt_f32_e32 v173, v165
	v_mul_f32_e32 v174, 0x4f800000, v163
	v_cmp_gt_f32_e64 s[2:3], s50, v163
	v_add_u32_e32 v175, 1, v173
	s_nop 0
	v_cndmask_b32_e64 v163, v163, v174, s[2:3]
	v_add_u32_e32 v174, -1, v173
	v_fma_f32 v176, -v174, v173, v165
	v_fma_f32 v177, -v175, v173, v165
	v_cmp_ge_f32_e64 s[4:5], 0, v176
	v_sqrt_f32_e32 v182, v163
	s_nop 0
	v_cndmask_b32_e64 v173, v173, v174, s[4:5]
	v_cmp_lt_f32_e64 s[4:5], 0, v177
	s_nop 1
	v_cndmask_b32_e64 v173, v173, v175, s[4:5]
	v_mul_f32_e32 v174, 0x37800000, v173
	v_cndmask_b32_e32 v173, v173, v174, vcc
	v_cmp_class_f32_e32 vcc, v165, v172
	s_nop 1
	v_cndmask_b32_e32 v165, v173, v165, vcc
	v_div_scale_f32 v173, s[4:5], v165, v165, 1.0
	v_rcp_f32_e32 v174, v173
	v_div_scale_f32 v175, vcc, 1.0, v165, 1.0
	v_fma_f32 v176, -v173, v174, 1.0
	v_fmac_f32_e32 v174, v176, v174
	v_mul_f32_e32 v176, v175, v174
	v_fma_f32 v177, -v173, v176, v175
	v_fmac_f32_e32 v176, v177, v174
	v_fma_f32 v173, -v173, v176, v175
	v_div_fmas_f32 v173, v173, v174, v176
	v_div_fixup_f32 v174, v173, v165, 1.0
	v_pk_mul_f32 v[126:127], v[126:127], v[174:175] op_sel_hi:[1,0]
	v_pk_mul_f32 v[128:129], v[128:129], v[174:175] op_sel_hi:[1,0]
	v_pk_mul_f32 v[124:125], v[124:125], v[174:175] op_sel_hi:[1,0]
	v_pk_mul_f32 v[122:123], v[122:123], v[174:175] op_sel_hi:[1,0]
	v_mul_f32_e32 v165, 0xbfb8aa3b, v126
	v_mul_f32_e32 v173, 0xbfb8aa3b, v127
	v_pk_mul_f32 v[118:119], v[118:119], v[174:175] op_sel_hi:[1,0]
	v_pk_mul_f32 v[120:121], v[120:121], v[174:175] op_sel_hi:[1,0]
	v_pk_mul_f32 v[114:115], v[114:115], v[174:175] op_sel_hi:[1,0]
	v_pk_mul_f32 v[116:117], v[116:117], v[174:175] op_sel_hi:[1,0]
	v_mul_f32_e32 v174, 0xbfb8aa3b, v128
	v_mul_f32_e32 v175, 0xbfb8aa3b, v129
	v_mul_f32_e32 v176, 0xbfb8aa3b, v122
	v_mul_f32_e32 v177, 0xbfb8aa3b, v123
	v_mul_f32_e32 v178, 0xbfb8aa3b, v124
	v_mul_f32_e32 v179, 0xbfb8aa3b, v125
	v_exp_f32_e32 v165, v165
	v_exp_f32_e32 v173, v173
	v_exp_f32_e32 v174, v174
	v_exp_f32_e32 v175, v175
	v_exp_f32_e32 v176, v176
	v_exp_f32_e32 v177, v177
	v_exp_f32_e32 v178, v178
	v_exp_f32_e32 v179, v179
	v_add_f32_e32 v165, 1.0, v165
	v_add_f32_e32 v173, 1.0, v173
	v_add_f32_e32 v180, 1.0, v174
	v_add_f32_e32 v181, 1.0, v175
	v_add_f32_e32 v183, 1.0, v176
	v_add_f32_e32 v184, 1.0, v177
	v_add_f32_e32 v185, 1.0, v178
	v_add_f32_e32 v186, 1.0, v179
	v_rcp_f32_e32 v174, v165
	v_rcp_f32_e32 v175, v173
	v_rcp_f32_e32 v176, v180
	v_rcp_f32_e32 v177, v181
	v_rcp_f32_e32 v178, v183
	v_rcp_f32_e32 v179, v184
	v_rcp_f32_e32 v180, v185
	v_rcp_f32_e32 v181, v186
	v_pk_mul_f32 v[126:127], v[126:127], v[174:175]
	v_pk_mul_f32 v[122:123], v[122:123], v[178:179]
	v_pk_mul_f32 v[118:119], v[118:119], v[126:127]
	v_pk_mul_f32 v[124:125], v[124:125], v[180:181]
	v_pk_mul_f32 v[128:129], v[128:129], v[176:177]
	v_pk_mul_f32 v[124:125], v[116:117], v[124:125]
	v_pk_mul_f32 v[116:117], v[114:115], v[122:123]
	v_cvt_pk_bf16_f32 v114, v118, v119
	v_add_u32_e32 v118, -1, v182
	v_fma_f32 v119, -v118, v182, v163
	v_pk_mul_f32 v[120:121], v[120:121], v[128:129]
	v_cmp_ge_f32_e32 vcc, 0, v119
	v_add_u32_e32 v119, 1, v182
	v_cvt_pk_bf16_f32 v115, v120, v121
	v_fma_f32 v120, -v119, v182, v163
	v_cndmask_b32_e32 v118, v182, v118, vcc
	v_cmp_lt_f32_e32 vcc, 0, v120
	v_cvt_pk_bf16_f32 v116, v116, v117
	v_cvt_pk_bf16_f32 v117, v124, v125
	s_nop 1
	v_cndmask_b32_e32 v118, v118, v119, vcc
	v_mul_f32_e32 v119, 0x37800000, v118
	v_cndmask_b32_e64 v118, v118, v119, s[2:3]
	v_cmp_class_f32_e32 vcc, v163, v172
	s_nop 1
	v_cndmask_b32_e32 v120, v118, v163, vcc
	v_div_scale_f32 v121, s[2:3], v120, v120, 1.0
	v_rcp_f32_e32 v122, v121
	v_mad_i64_i32 v[118:119], s[2:3], v164, s51, v[150:151]
	global_store_dwordx4 v[118:119], v[114:117], off
	s_nop 1
	v_fma_f32 v114, -v121, v122, 1.0
	v_fmac_f32_e32 v122, v114, v122
	v_div_scale_f32 v114, vcc, 1.0, v120, 1.0
	v_mul_f32_e32 v115, v114, v122
	v_fma_f32 v116, -v121, v115, v114
	v_fmac_f32_e32 v115, v116, v122
	v_fma_f32 v114, -v121, v115, v114
	v_div_fmas_f32 v114, v114, v122, v115
	v_div_fixup_f32 v114, v114, v120, 1.0
	v_pk_mul_f32 v[110:111], v[110:111], v[114:115] op_sel_hi:[1,0]
; __device__ __forceinline__ u32x4 pack8f(f32x4 a, f32x4 b) { u32x4 w; w.x = cvtpk(a[0], a[1]); w.y = cvtpk(a[2], a[3]); w.z = cvtpk(b[0], b[1]); w.w = cvtpk(b[2], b[3]); return w; }
; __device__ __forceinline__ f32x4 sig4(f32x4 v) { return (f32x4){sigmoidf_(v[0]), sigmoidf_(v[1]), sigmoidf_(v[2]), sigmoidf_(v[3])}; }
;     __device__ __forceinline__ void operator()(const f32x4 (&acc)[2][2][4][2], const Unit& u, int wr, int wc, int fr, int fq) const {
;     ...
;         EPI_ROWS_BEGIN
;             const float r = 1.0f / sqrtf(sq[ai][m] * (1.f / 4096.f) + EPS);
;             const f32x4 g0 = acc[ai][0][m][0] * r, g1 = acc[ai][0][m][1] * r;
;             *(u32x4*)(base + row * DFF) = pack8f(g0 * sig4(g0) * (acc[ai][1][m][0] * r), g1 * sig4(g1) * (acc[ai][1][m][1] * r));
;         EPI_ROWS_END
	s_nop 0
	v_mul_f32_e32 v115, 0xbfb8aa3b, v110
	v_exp_f32_e32 v115, v115
	v_mul_f32_e32 v116, 0xbfb8aa3b, v111
	v_exp_f32_e32 v117, v116
	v_pk_mul_f32 v[112:113], v[112:113], v[114:115] op_sel_hi:[1,0]
	v_add_f32_e32 v115, 1.0, v115
	v_rcp_f32_e32 v116, v115
	v_add_f32_e32 v115, 1.0, v117
	v_mul_f32_e32 v117, 0xbfb8aa3b, v112
	v_exp_f32_e32 v118, v117
	v_mul_f32_e32 v117, 0xbfb8aa3b, v113
	v_exp_f32_e32 v119, v117
	v_rcp_f32_e32 v117, v115
	v_add_f32_e32 v115, 1.0, v118
	v_rcp_f32_e32 v118, v115
	v_add_f32_e32 v115, 1.0, v119
	v_pk_mul_f32 v[106:107], v[106:107], v[114:115] op_sel_hi:[1,0]
	v_rcp_f32_e32 v119, v115
	v_pk_mul_f32 v[108:109], v[108:109], v[114:115] op_sel_hi:[1,0]
	v_pk_mul_f32 v[102:103], v[102:103], v[114:115] op_sel_hi:[1,0]
	v_mul_f32_e32 v115, 0xbfb8aa3b, v106
	v_pk_mul_f32 v[110:111], v[110:111], v[116:117]
	v_exp_f32_e32 v115, v115
	v_mul_f32_e32 v116, 0xbfb8aa3b, v107
	v_exp_f32_e32 v117, v116
	v_pk_mul_f32 v[112:113], v[112:113], v[118:119]
	v_pk_mul_f32 v[104:105], v[104:105], v[114:115] op_sel_hi:[1,0]
	v_add_f32_e32 v115, 1.0, v115
	v_rcp_f32_e32 v116, v115
	v_add_f32_e32 v115, 1.0, v117
	v_mul_f32_e32 v117, 0xbfb8aa3b, v108
	v_exp_f32_e32 v118, v117
	v_mul_f32_e32 v117, 0xbfb8aa3b, v109
	v_exp_f32_e32 v119, v117
	v_rcp_f32_e32 v117, v115
	v_add_f32_e32 v115, 1.0, v118
	v_rcp_f32_e32 v118, v115
	v_add_f32_e32 v115, 1.0, v119
	v_rcp_f32_e32 v119, v115
	v_pk_mul_f32 v[106:107], v[106:107], v[116:117]
	v_pk_mul_f32 v[98:99], v[98:99], v[114:115] op_sel_hi:[1,0]
	v_pk_mul_f32 v[100:101], v[100:101], v[114:115] op_sel_hi:[1,0]
	v_pk_mul_f32 v[108:109], v[108:109], v[118:119]
	v_pk_mul_f32 v[102:103], v[102:103], v[110:111]
	v_pk_mul_f32 v[108:109], v[100:101], v[108:109]
	v_pk_mul_f32 v[100:101], v[98:99], v[106:107]
	v_fmamk_f32 v99, v159, 0x39800000, v171
	v_cvt_pk_bf16_f32 v98, v102, v103
	v_mul_f32_e32 v102, 0x4f800000, v99
	v_cmp_gt_f32_e32 vcc, s50, v99
	v_pk_mul_f32 v[104:105], v[104:105], v[112:113]
	s_nop 0
	v_cndmask_b32_e32 v102, v99, v102, vcc
	v_sqrt_f32_e32 v103, v102
	v_cvt_pk_bf16_f32 v99, v104, v105
	v_cvt_pk_bf16_f32 v100, v100, v101
	v_cvt_pk_bf16_f32 v101, v108, v109
	s_nop 0
	v_add_u32_e32 v104, -1, v103
	v_fma_f32 v105, -v104, v103, v102
	v_cmp_ge_f32_e64 s[2:3], 0, v105
	v_add_u32_e32 v105, 1, v103
	s_nop 0
	v_cndmask_b32_e64 v104, v103, v104, s[2:3]
	v_fma_f32 v103, -v105, v103, v102
	v_cmp_lt_f32_e64 s[2:3], 0, v103
	s_nop 1
	v_cndmask_b32_e64 v103, v104, v105, s[2:3]
	v_mul_f32_e32 v104, 0x37800000, v103
	v_cndmask_b32_e32 v103, v103, v104, vcc
	v_cmp_class_f32_e32 vcc, v102, v172
	s_nop 1
	v_cndmask_b32_e32 v104, v103, v102, vcc
	v_div_scale_f32 v105, s[2:3], v104, v104, 1.0
	v_rcp_f32_e32 v106, v105
	v_mad_i64_i32 v[102:103], s[2:3], v162, s51, v[150:151]
	global_store_dwordx4 v[102:103], v[98:101], off
	s_nop 1
	v_fma_f32 v98, -v105, v106, 1.0
	v_fmac_f32_e32 v106, v98, v106
	v_div_scale_f32 v98, vcc, 1.0, v104, 1.0
	v_mul_f32_e32 v99, v98, v106
	v_fma_f32 v100, -v105, v99, v98
	v_fmac_f32_e32 v99, v100, v106
	v_fma_f32 v98, -v105, v99, v98
	v_div_fmas_f32 v98, v98, v106, v99
	v_div_fixup_f32 v98, v98, v104, 1.0
	v_pk_mul_f32 v[94:95], v[94:95], v[98:99] op_sel_hi:[1,0]
	s_nop 0
	v_mul_f32_e32 v99, 0xbfb8aa3b, v94
	v_exp_f32_e32 v99, v99
	v_mul_f32_e32 v100, 0xbfb8aa3b, v95
	v_exp_f32_e32 v101, v100
	v_pk_mul_f32 v[96:97], v[96:97], v[98:99] op_sel_hi:[1,0]
	v_add_f32_e32 v99, 1.0, v99
	v_rcp_f32_e32 v100, v99
	v_add_f32_e32 v99, 1.0, v101
	v_mul_f32_e32 v101, 0xbfb8aa3b, v96
	v_exp_f32_e32 v102, v101
	v_mul_f32_e32 v101, 0xbfb8aa3b, v97
	v_exp_f32_e32 v103, v101
	v_rcp_f32_e32 v101, v99
	v_add_f32_e32 v99, 1.0, v102
	v_rcp_f32_e32 v102, v99
	v_add_f32_e32 v99, 1.0, v103
	v_pk_mul_f32 v[90:91], v[90:91], v[98:99] op_sel_hi:[1,0]
	v_rcp_f32_e32 v103, v99
	v_pk_mul_f32 v[92:93], v[92:93], v[98:99] op_sel_hi:[1,0]
	v_pk_mul_f32 v[86:87], v[86:87], v[98:99] op_sel_hi:[1,0]
	v_mul_f32_e32 v99, 0xbfb8aa3b, v90
	v_pk_mul_f32 v[94:95], v[94:95], v[100:101]
	v_exp_f32_e32 v99, v99
	v_mul_f32_e32 v100, 0xbfb8aa3b, v91
	v_exp_f32_e32 v101, v100
	v_pk_mul_f32 v[96:97], v[96:97], v[102:103]
	v_pk_mul_f32 v[88:89], v[88:89], v[98:99] op_sel_hi:[1,0]
	v_add_f32_e32 v99, 1.0, v99
	v_rcp_f32_e32 v100, v99
	v_add_f32_e32 v99, 1.0, v101
	v_mul_f32_e32 v101, 0xbfb8aa3b, v92
	v_exp_f32_e32 v102, v101
	v_mul_f32_e32 v101, 0xbfb8aa3b, v93
	v_exp_f32_e32 v103, v101
	v_rcp_f32_e32 v101, v99
	v_add_f32_e32 v99, 1.0, v102
	v_rcp_f32_e32 v102, v99
	v_add_f32_e32 v99, 1.0, v103
	v_rcp_f32_e32 v103, v99
	v_pk_mul_f32 v[90:91], v[90:91], v[100:101]
	v_pk_mul_f32 v[82:83], v[82:83], v[98:99] op_sel_hi:[1,0]
	v_pk_mul_f32 v[84:85], v[84:85], v[98:99] op_sel_hi:[1,0]
	v_pk_mul_f32 v[92:93], v[92:93], v[102:103]
	v_pk_mul_f32 v[86:87], v[86:87], v[94:95]
	v_pk_mul_f32 v[92:93], v[84:85], v[92:93]
	v_pk_mul_f32 v[84:85], v[82:83], v[90:91]
	v_fmamk_f32 v83, v161, 0x39800000, v171
	v_cvt_pk_bf16_f32 v82, v86, v87
	v_mul_f32_e32 v86, 0x4f800000, v83
	v_cmp_gt_f32_e32 vcc, s50, v83
	v_pk_mul_f32 v[88:89], v[88:89], v[96:97]
	s_nop 0
	v_cndmask_b32_e32 v86, v83, v86, vcc
	v_sqrt_f32_e32 v87, v86
	v_cvt_pk_bf16_f32 v83, v88, v89
	v_cvt_pk_bf16_f32 v84, v84, v85
	v_cvt_pk_bf16_f32 v85, v92, v93
	s_nop 0
	v_add_u32_e32 v88, -1, v87
	v_fma_f32 v89, -v88, v87, v86
	v_cmp_ge_f32_e64 s[2:3], 0, v89
	v_add_u32_e32 v89, 1, v87
	s_nop 0
	v_cndmask_b32_e64 v88, v87, v88, s[2:3]
	v_fma_f32 v87, -v89, v87, v86
	v_cmp_lt_f32_e64 s[2:3], 0, v87
	s_nop 1
	v_cndmask_b32_e64 v87, v88, v89, s[2:3]
	v_mul_f32_e32 v88, 0x37800000, v87
	v_cndmask_b32_e32 v87, v87, v88, vcc
	v_cmp_class_f32_e32 vcc, v86, v172
	s_nop 1
	v_cndmask_b32_e32 v88, v87, v86, vcc
; __device__ __forceinline__ u32x4 pack8f(f32x4 a, f32x4 b) { u32x4 w; w.x = cvtpk(a[0], a[1]); w.y = cvtpk(a[2], a[3]); w.z = cvtpk(b[0], b[1]); w.w = cvtpk(b[2], b[3]); return w; }
; __device__ __forceinline__ f32x4 sig4(f32x4 v) { return (f32x4){sigmoidf_(v[0]), sigmoidf_(v[1]), sigmoidf_(v[2]), sigmoidf_(v[3])}; }
; __device__ __forceinline__ float sigmoidf_(float x) { return __builtin_amdgcn_rcpf(1.0f + __builtin_amdgcn_exp2f(-1.4426950408889634f * x)); }
;     __device__ __forceinline__ void operator()(const f32x4 (&acc)[2][2][4][2], const Unit& u, int wr, int wc, int fr, int fq) const {
;     ...
;         EPI_ROWS_BEGIN
;             const float r = 1.0f / sqrtf(sq[ai][m] * (1.f / 4096.f) + EPS);
;             const f32x4 g0 = acc[ai][0][m][0] * r, g1 = acc[ai][0][m][1] * r;
;             *(u32x4*)(base + row * DFF) = pack8f(g0 * sig4(g0) * (acc[ai][1][m][0] * r), g1 * sig4(g1) * (acc[ai][1][m][1] * r));
;         EPI_ROWS_END
	v_div_scale_f32 v89, s[2:3], v88, v88, 1.0
	v_rcp_f32_e32 v90, v89
	v_mad_i64_i32 v[86:87], s[2:3], v160, s51, v[150:151]
	global_store_dwordx4 v[86:87], v[82:85], off
	s_nop 1
	v_fma_f32 v82, -v89, v90, 1.0
	v_fmac_f32_e32 v90, v82, v90
	v_div_scale_f32 v82, vcc, 1.0, v88, 1.0
	v_mul_f32_e32 v83, v82, v90
	v_fma_f32 v84, -v89, v83, v82
	v_fmac_f32_e32 v83, v84, v90
	v_fma_f32 v82, -v89, v83, v82
	v_div_fmas_f32 v82, v82, v90, v83
	v_div_fixup_f32 v82, v82, v88, 1.0
	v_pk_mul_f32 v[78:79], v[78:79], v[82:83] op_sel_hi:[1,0]
	s_nop 0
	v_mul_f32_e32 v83, 0xbfb8aa3b, v78
	v_exp_f32_e32 v83, v83
	v_mul_f32_e32 v84, 0xbfb8aa3b, v79
	v_exp_f32_e32 v85, v84
	v_pk_mul_f32 v[80:81], v[80:81], v[82:83] op_sel_hi:[1,0]
	v_add_f32_e32 v83, 1.0, v83
	v_rcp_f32_e32 v84, v83
	v_add_f32_e32 v83, 1.0, v85
	v_mul_f32_e32 v85, 0xbfb8aa3b, v80
	v_exp_f32_e32 v86, v85
	v_mul_f32_e32 v85, 0xbfb8aa3b, v81
	v_exp_f32_e32 v87, v85
	v_rcp_f32_e32 v85, v83
	v_add_f32_e32 v83, 1.0, v86
	v_rcp_f32_e32 v86, v83
	v_add_f32_e32 v83, 1.0, v87
	v_pk_mul_f32 v[74:75], v[74:75], v[82:83] op_sel_hi:[1,0]
	v_rcp_f32_e32 v87, v83
	v_pk_mul_f32 v[76:77], v[76:77], v[82:83] op_sel_hi:[1,0]
	v_pk_mul_f32 v[70:71], v[70:71], v[82:83] op_sel_hi:[1,0]
	v_mul_f32_e32 v83, 0xbfb8aa3b, v74
	v_pk_mul_f32 v[78:79], v[78:79], v[84:85]
	v_exp_f32_e32 v83, v83
	v_mul_f32_e32 v84, 0xbfb8aa3b, v75
	v_exp_f32_e32 v85, v84
	v_pk_mul_f32 v[80:81], v[80:81], v[86:87]
	v_pk_mul_f32 v[72:73], v[72:73], v[82:83] op_sel_hi:[1,0]
	v_add_f32_e32 v83, 1.0, v83
	v_rcp_f32_e32 v84, v83
	v_add_f32_e32 v83, 1.0, v85
	v_mul_f32_e32 v85, 0xbfb8aa3b, v76
	v_exp_f32_e32 v86, v85
	v_mul_f32_e32 v85, 0xbfb8aa3b, v77
	v_exp_f32_e32 v87, v85
	v_rcp_f32_e32 v85, v83
	v_add_f32_e32 v83, 1.0, v86
	v_rcp_f32_e32 v86, v83
	v_add_f32_e32 v83, 1.0, v87
	v_rcp_f32_e32 v87, v83
	v_pk_mul_f32 v[74:75], v[74:75], v[84:85]
	v_pk_mul_f32 v[66:67], v[66:67], v[82:83] op_sel_hi:[1,0]
	v_pk_mul_f32 v[68:69], v[68:69], v[82:83] op_sel_hi:[1,0]
	v_pk_mul_f32 v[76:77], v[76:77], v[86:87]
	v_pk_mul_f32 v[70:71], v[70:71], v[78:79]
	v_pk_mul_f32 v[76:77], v[68:69], v[76:77]
	v_pk_mul_f32 v[68:69], v[66:67], v[74:75]
	v_fmamk_f32 v67, v157, 0x39800000, v171
	v_cvt_pk_bf16_f32 v66, v70, v71
	v_mul_f32_e32 v70, 0x4f800000, v67
	v_cmp_gt_f32_e32 vcc, s50, v67
	v_pk_mul_f32 v[72:73], v[72:73], v[80:81]
	s_nop 0
	v_cndmask_b32_e32 v70, v67, v70, vcc
	v_sqrt_f32_e32 v71, v70
	v_cvt_pk_bf16_f32 v67, v72, v73
	v_cvt_pk_bf16_f32 v68, v68, v69
	v_cvt_pk_bf16_f32 v69, v76, v77
	s_nop 0
	v_add_u32_e32 v72, -1, v71
	v_fma_f32 v73, -v72, v71, v70
	v_cmp_ge_f32_e64 s[2:3], 0, v73
	v_add_u32_e32 v73, 1, v71
	s_nop 0
	v_cndmask_b32_e64 v72, v71, v72, s[2:3]
	v_fma_f32 v71, -v73, v71, v70
	v_cmp_lt_f32_e64 s[2:3], 0, v71
	s_nop 1
	v_cndmask_b32_e64 v71, v72, v73, s[2:3]
	v_mul_f32_e32 v72, 0x37800000, v71
	v_cndmask_b32_e32 v71, v71, v72, vcc
	v_cmp_class_f32_e32 vcc, v70, v172
	s_nop 1
	v_cndmask_b32_e32 v72, v71, v70, vcc
	v_div_scale_f32 v73, s[2:3], v72, v72, 1.0
	v_rcp_f32_e32 v74, v73
	v_mad_i64_i32 v[70:71], s[2:3], v158, s51, v[150:151]
	global_store_dwordx4 v[70:71], v[66:69], off
	s_nop 1
	v_fma_f32 v66, -v73, v74, 1.0
	v_fmac_f32_e32 v74, v66, v74
	v_div_scale_f32 v66, vcc, 1.0, v72, 1.0
	v_mul_f32_e32 v67, v66, v74
	v_fma_f32 v68, -v73, v67, v66
	v_fmac_f32_e32 v67, v68, v74
	v_fma_f32 v66, -v73, v67, v66
	v_div_fmas_f32 v66, v66, v74, v67
	v_div_fixup_f32 v66, v66, v72, 1.0
	v_pk_mul_f32 v[62:63], v[62:63], v[66:67] op_sel_hi:[1,0]
	s_nop 0
	v_mul_f32_e32 v67, 0xbfb8aa3b, v62
	v_exp_f32_e32 v67, v67
	v_mul_f32_e32 v68, 0xbfb8aa3b, v63
	v_exp_f32_e32 v69, v68
	v_pk_mul_f32 v[64:65], v[64:65], v[66:67] op_sel_hi:[1,0]
	v_add_f32_e32 v67, 1.0, v67
	v_rcp_f32_e32 v68, v67
	v_add_f32_e32 v67, 1.0, v69
	v_mul_f32_e32 v69, 0xbfb8aa3b, v64
	v_exp_f32_e32 v70, v69
	v_mul_f32_e32 v69, 0xbfb8aa3b, v65
	v_exp_f32_e32 v71, v69
	v_rcp_f32_e32 v69, v67
	v_add_f32_e32 v67, 1.0, v70
	v_rcp_f32_e32 v70, v67
	v_add_f32_e32 v67, 1.0, v71
	v_pk_mul_f32 v[58:59], v[58:59], v[66:67] op_sel_hi:[1,0]
	v_rcp_f32_e32 v71, v67
	v_pk_mul_f32 v[60:61], v[60:61], v[66:67] op_sel_hi:[1,0]
	v_pk_mul_f32 v[54:55], v[54:55], v[66:67] op_sel_hi:[1,0]
	v_mul_f32_e32 v67, 0xbfb8aa3b, v58
	v_pk_mul_f32 v[62:63], v[62:63], v[68:69]
	v_exp_f32_e32 v67, v67
	v_mul_f32_e32 v68, 0xbfb8aa3b, v59
	v_exp_f32_e32 v69, v68
	v_pk_mul_f32 v[64:65], v[64:65], v[70:71]
	v_pk_mul_f32 v[56:57], v[56:57], v[66:67] op_sel_hi:[1,0]
	v_add_f32_e32 v67, 1.0, v67
	v_rcp_f32_e32 v68, v67
	v_add_f32_e32 v67, 1.0, v69
	v_mul_f32_e32 v69, 0xbfb8aa3b, v60
	v_exp_f32_e32 v70, v69
	v_mul_f32_e32 v69, 0xbfb8aa3b, v61
	v_exp_f32_e32 v71, v69
	v_rcp_f32_e32 v69, v67
	v_add_f32_e32 v67, 1.0, v70
	v_rcp_f32_e32 v70, v67
	v_add_f32_e32 v67, 1.0, v71
	v_rcp_f32_e32 v71, v67
	v_pk_mul_f32 v[58:59], v[58:59], v[68:69]
	v_pk_mul_f32 v[50:51], v[50:51], v[66:67] op_sel_hi:[1,0]
	v_pk_mul_f32 v[52:53], v[52:53], v[66:67] op_sel_hi:[1,0]
	v_pk_mul_f32 v[60:61], v[60:61], v[70:71]
	v_pk_mul_f32 v[54:55], v[54:55], v[62:63]
	v_pk_mul_f32 v[60:61], v[52:53], v[60:61]
	v_pk_mul_f32 v[52:53], v[50:51], v[58:59]
	v_fmamk_f32 v51, v155, 0x39800000, v171
	v_cvt_pk_bf16_f32 v50, v54, v55
	v_mul_f32_e32 v54, 0x4f800000, v51
	v_cmp_gt_f32_e32 vcc, s50, v51
	v_pk_mul_f32 v[56:57], v[56:57], v[64:65]
	s_nop 0
	v_cndmask_b32_e32 v54, v51, v54, vcc
	v_sqrt_f32_e32 v55, v54
	v_cvt_pk_bf16_f32 v51, v56, v57
	v_cvt_pk_bf16_f32 v52, v52, v53
	v_cvt_pk_bf16_f32 v53, v60, v61
	s_nop 0
	v_add_u32_e32 v56, -1, v55
	v_fma_f32 v57, -v56, v55, v54
	v_cmp_ge_f32_e64 s[2:3], 0, v57
	v_add_u32_e32 v57, 1, v55
	s_nop 0
	v_cndmask_b32_e64 v56, v55, v56, s[2:3]
; __device__ __forceinline__ u32x4 pack8f(f32x4 a, f32x4 b) { u32x4 w; w.x = cvtpk(a[0], a[1]); w.y = cvtpk(a[2], a[3]); w.z = cvtpk(b[0], b[1]); w.w = cvtpk(b[2], b[3]); return w; }
; __device__ __forceinline__ f32x4 sig4(f32x4 v) { return (f32x4){sigmoidf_(v[0]), sigmoidf_(v[1]), sigmoidf_(v[2]), sigmoidf_(v[3])}; }
; __device__ __forceinline__ float sigmoidf_(float x) { return __builtin_amdgcn_rcpf(1.0f + __builtin_amdgcn_exp2f(-1.4426950408889634f * x)); }
;     __device__ __forceinline__ void operator()(const f32x4 (&acc)[2][2][4][2], const Unit& u, int wr, int wc, int fr, int fq) const {
;     ...
;         EPI_ROWS_BEGIN
;             const float r = 1.0f / sqrtf(sq[ai][m] * (1.f / 4096.f) + EPS);
;             const f32x4 g0 = acc[ai][0][m][0] * r, g1 = acc[ai][0][m][1] * r;
;             *(u32x4*)(base + row * DFF) = pack8f(g0 * sig4(g0) * (acc[ai][1][m][0] * r), g1 * sig4(g1) * (acc[ai][1][m][1] * r));
;         EPI_ROWS_END
	v_fma_f32 v55, -v57, v55, v54
	v_cmp_lt_f32_e64 s[2:3], 0, v55
	s_nop 1
	v_cndmask_b32_e64 v55, v56, v57, s[2:3]
	v_mul_f32_e32 v56, 0x37800000, v55
	v_cndmask_b32_e32 v55, v55, v56, vcc
	v_cmp_class_f32_e32 vcc, v54, v172
	s_nop 1
	v_cndmask_b32_e32 v56, v55, v54, vcc
	v_div_scale_f32 v57, s[2:3], v56, v56, 1.0
	v_rcp_f32_e32 v58, v57
	v_mad_i64_i32 v[54:55], s[2:3], v156, s51, v[150:151]
	global_store_dwordx4 v[54:55], v[50:53], off
	s_nop 1
	v_fma_f32 v50, -v57, v58, 1.0
	v_fmac_f32_e32 v58, v50, v58
	v_div_scale_f32 v50, vcc, 1.0, v56, 1.0
	v_mul_f32_e32 v51, v50, v58
	v_fma_f32 v52, -v57, v51, v50
	v_fmac_f32_e32 v51, v52, v58
	v_fma_f32 v50, -v57, v51, v50
	v_div_fmas_f32 v50, v50, v58, v51
	v_div_fixup_f32 v50, v50, v56, 1.0
	v_pk_mul_f32 v[46:47], v[46:47], v[50:51] op_sel_hi:[1,0]
	s_nop 0
	v_mul_f32_e32 v51, 0xbfb8aa3b, v46
	v_exp_f32_e32 v51, v51
	v_mul_f32_e32 v52, 0xbfb8aa3b, v47
	v_exp_f32_e32 v53, v52
	v_pk_mul_f32 v[48:49], v[48:49], v[50:51] op_sel_hi:[1,0]
	v_add_f32_e32 v51, 1.0, v51
	v_rcp_f32_e32 v52, v51
	v_add_f32_e32 v51, 1.0, v53
	v_mul_f32_e32 v53, 0xbfb8aa3b, v48
	v_exp_f32_e32 v54, v53
	v_mul_f32_e32 v53, 0xbfb8aa3b, v49
	v_exp_f32_e32 v55, v53
	v_rcp_f32_e32 v53, v51
	v_add_f32_e32 v51, 1.0, v54
	v_rcp_f32_e32 v54, v51
	v_add_f32_e32 v51, 1.0, v55
	v_pk_mul_f32 v[42:43], v[42:43], v[50:51] op_sel_hi:[1,0]
	v_rcp_f32_e32 v55, v51
	v_pk_mul_f32 v[44:45], v[44:45], v[50:51] op_sel_hi:[1,0]
	v_pk_mul_f32 v[38:39], v[38:39], v[50:51] op_sel_hi:[1,0]
	v_mul_f32_e32 v51, 0xbfb8aa3b, v42
	v_pk_mul_f32 v[46:47], v[46:47], v[52:53]
	v_exp_f32_e32 v51, v51
	v_mul_f32_e32 v52, 0xbfb8aa3b, v43
	v_exp_f32_e32 v53, v52
	v_pk_mul_f32 v[48:49], v[48:49], v[54:55]
	v_pk_mul_f32 v[40:41], v[40:41], v[50:51] op_sel_hi:[1,0]
	v_add_f32_e32 v51, 1.0, v51
	v_rcp_f32_e32 v52, v51
	v_add_f32_e32 v51, 1.0, v53
	v_mul_f32_e32 v53, 0xbfb8aa3b, v44
	v_exp_f32_e32 v54, v53
	v_mul_f32_e32 v53, 0xbfb8aa3b, v45
	v_exp_f32_e32 v55, v53
	v_rcp_f32_e32 v53, v51
	v_add_f32_e32 v51, 1.0, v54
	v_rcp_f32_e32 v54, v51
	v_add_f32_e32 v51, 1.0, v55
	v_rcp_f32_e32 v55, v51
	v_pk_mul_f32 v[42:43], v[42:43], v[52:53]
	v_pk_mul_f32 v[34:35], v[34:35], v[50:51] op_sel_hi:[1,0]
	v_pk_mul_f32 v[36:37], v[36:37], v[50:51] op_sel_hi:[1,0]
	v_pk_mul_f32 v[44:45], v[44:45], v[54:55]
	v_pk_mul_f32 v[38:39], v[38:39], v[46:47]
	v_pk_mul_f32 v[44:45], v[36:37], v[44:45]
	v_pk_mul_f32 v[36:37], v[34:35], v[42:43]
	v_fmamk_f32 v35, v153, 0x39800000, v171
	v_cvt_pk_bf16_f32 v34, v38, v39
	v_mul_f32_e32 v38, 0x4f800000, v35
	v_cmp_gt_f32_e32 vcc, s50, v35
	v_pk_mul_f32 v[40:41], v[40:41], v[48:49]
	s_nop 0
	v_cndmask_b32_e32 v38, v35, v38, vcc
	v_sqrt_f32_e32 v39, v38
	v_cvt_pk_bf16_f32 v35, v40, v41
	v_cvt_pk_bf16_f32 v36, v36, v37
	v_cvt_pk_bf16_f32 v37, v44, v45
	s_nop 0
	v_add_u32_e32 v40, -1, v39
	v_fma_f32 v41, -v40, v39, v38
	v_cmp_ge_f32_e64 s[2:3], 0, v41
	v_add_u32_e32 v41, 1, v39
	s_nop 0
	v_cndmask_b32_e64 v40, v39, v40, s[2:3]
	v_fma_f32 v39, -v41, v39, v38
	v_cmp_lt_f32_e64 s[2:3], 0, v39
	s_nop 1
	v_cndmask_b32_e64 v39, v40, v41, s[2:3]
	v_mul_f32_e32 v40, 0x37800000, v39
	v_cndmask_b32_e32 v39, v39, v40, vcc
	v_cmp_class_f32_e32 vcc, v38, v172
	s_nop 1
	v_cndmask_b32_e32 v40, v39, v38, vcc
	v_div_scale_f32 v41, s[2:3], v40, v40, 1.0
	v_rcp_f32_e32 v42, v41
	v_mad_i64_i32 v[38:39], s[2:3], v154, s51, v[150:151]
	global_store_dwordx4 v[38:39], v[34:37], off
	s_nop 1
	v_fma_f32 v34, -v41, v42, 1.0
	v_fmac_f32_e32 v42, v34, v42
	v_div_scale_f32 v34, vcc, 1.0, v40, 1.0
	v_mul_f32_e32 v35, v34, v42
	v_fma_f32 v36, -v41, v35, v34
	v_fmac_f32_e32 v35, v36, v42
	v_fma_f32 v34, -v41, v35, v34
	v_div_fmas_f32 v34, v34, v42, v35
	v_div_fixup_f32 v34, v34, v40, 1.0
	v_pk_mul_f32 v[30:31], v[30:31], v[34:35] op_sel_hi:[1,0]
	s_nop 0
	v_mul_f32_e32 v35, 0xbfb8aa3b, v30
	v_exp_f32_e32 v35, v35
	v_mul_f32_e32 v36, 0xbfb8aa3b, v31
	v_exp_f32_e32 v37, v36
	v_pk_mul_f32 v[32:33], v[32:33], v[34:35] op_sel_hi:[1,0]
	v_add_f32_e32 v35, 1.0, v35
	v_rcp_f32_e32 v36, v35
	v_add_f32_e32 v35, 1.0, v37
	v_mul_f32_e32 v37, 0xbfb8aa3b, v32
	v_exp_f32_e32 v38, v37
	v_mul_f32_e32 v37, 0xbfb8aa3b, v33
	v_exp_f32_e32 v39, v37
	v_rcp_f32_e32 v37, v35
	v_add_f32_e32 v35, 1.0, v38
	v_rcp_f32_e32 v38, v35
	v_add_f32_e32 v35, 1.0, v39
	v_pk_mul_f32 v[26:27], v[26:27], v[34:35] op_sel_hi:[1,0]
	v_rcp_f32_e32 v39, v35
	v_pk_mul_f32 v[28:29], v[28:29], v[34:35] op_sel_hi:[1,0]
; #define PG8_BAR __builtin_amdgcn_s_barrier()
; __device__ __forceinline__ u32x4 pack8f(f32x4 a, f32x4 b) { u32x4 w; w.x = cvtpk(a[0], a[1]); w.y = cvtpk(a[2], a[3]); w.z = cvtpk(b[0], b[1]); w.w = cvtpk(b[2], b[3]); return w; }
; __device__ __forceinline__ f32x4 sig4(f32x4 v) { return (f32x4){sigmoidf_(v[0]), sigmoidf_(v[1]), sigmoidf_(v[2]), sigmoidf_(v[3])}; }
; template <class Epi, class Sched, bool ALIGN_EPI = true, bool SP2 = true>
; __device__ __forceinline__ void gemm_phase(LAS unsigned char* lds, const Gemm g, const Sched& S, const Epi& E) {
;     ...
;         if constexpr (ALIGN_EPI) { if (wr == 0) PG8_BAR; }
;         E(acc, cur, wr, wc, fr, fq);
;         if (!has_next) break;
; #pragma unroll
;         for (int a = 0; a < 2; ++a)
; #pragma unroll
;             for (int b = 0; b < 2; ++b)
; #pragma unroll
;                 for (int m = 0; m < 4; ++m)
; #pragma unroll
;                     for (int n = 0; n < 2; ++n) acc[a][b][m][n] = (f32x4){0.f, 0.f, 0.f, 0.f};
;         cur = nxt; cA = nA; cB = nB; ++ui;
;         if constexpr (ALIGN_EPI) { if (wr == 1) PG8_BAR; }
;     __device__ __forceinline__ void operator()(const f32x4 (&acc)[2][2][4][2], const Unit& u, int wr, int wc, int fr, int fq) const {
;     ...
;         EPI_ROWS_BEGIN
;             const float r = 1.0f / sqrtf(sq[ai][m] * (1.f / 4096.f) + EPS);
;             const f32x4 g0 = acc[ai][0][m][0] * r, g1 = acc[ai][0][m][1] * r;
;             *(u32x4*)(base + row * DFF) = pack8f(g0 * sig4(g0) * (acc[ai][1][m][0] * r), g1 * sig4(g1) * (acc[ai][1][m][1] * r));
;         EPI_ROWS_END
	v_pk_mul_f32 v[22:23], v[22:23], v[34:35] op_sel_hi:[1,0]
	v_mul_f32_e32 v35, 0xbfb8aa3b, v26
	v_pk_mul_f32 v[30:31], v[30:31], v[36:37]
	v_exp_f32_e32 v35, v35
	v_mul_f32_e32 v36, 0xbfb8aa3b, v27
	v_exp_f32_e32 v37, v36
	v_pk_mul_f32 v[32:33], v[32:33], v[38:39]
	v_pk_mul_f32 v[24:25], v[24:25], v[34:35] op_sel_hi:[1,0]
	v_add_f32_e32 v35, 1.0, v35
	v_rcp_f32_e32 v36, v35
	v_add_f32_e32 v35, 1.0, v37
	v_mul_f32_e32 v37, 0xbfb8aa3b, v28
	v_exp_f32_e32 v38, v37
	v_mul_f32_e32 v37, 0xbfb8aa3b, v29
	v_exp_f32_e32 v39, v37
	v_rcp_f32_e32 v37, v35
	v_add_f32_e32 v35, 1.0, v38
	v_rcp_f32_e32 v38, v35
	v_add_f32_e32 v35, 1.0, v39
	v_rcp_f32_e32 v39, v35
	v_pk_mul_f32 v[26:27], v[26:27], v[36:37]
	v_pk_mul_f32 v[18:19], v[18:19], v[34:35] op_sel_hi:[1,0]
	v_pk_mul_f32 v[20:21], v[20:21], v[34:35] op_sel_hi:[1,0]
	v_pk_mul_f32 v[28:29], v[28:29], v[38:39]
	v_pk_mul_f32 v[22:23], v[22:23], v[30:31]
	v_pk_mul_f32 v[28:29], v[20:21], v[28:29]
	v_pk_mul_f32 v[20:21], v[18:19], v[26:27]
	v_fmamk_f32 v19, v149, 0x39800000, v171
	v_cvt_pk_bf16_f32 v18, v22, v23
	v_mul_f32_e32 v22, 0x4f800000, v19
	v_cmp_gt_f32_e32 vcc, s50, v19
	v_pk_mul_f32 v[24:25], v[24:25], v[32:33]
	s_nop 0
	v_cndmask_b32_e32 v22, v19, v22, vcc
	v_sqrt_f32_e32 v23, v22
	v_cvt_pk_bf16_f32 v19, v24, v25
	v_cvt_pk_bf16_f32 v20, v20, v21
	v_cvt_pk_bf16_f32 v21, v28, v29
	s_nop 0
	v_add_u32_e32 v24, -1, v23
	v_fma_f32 v25, -v24, v23, v22
	v_cmp_ge_f32_e64 s[2:3], 0, v25
	v_add_u32_e32 v25, 1, v23
	s_nop 0
	v_cndmask_b32_e64 v24, v23, v24, s[2:3]
	v_fma_f32 v23, -v25, v23, v22
	v_cmp_lt_f32_e64 s[2:3], 0, v23
	s_nop 1
	v_cndmask_b32_e64 v23, v24, v25, s[2:3]
	v_mul_f32_e32 v24, 0x37800000, v23
	v_cndmask_b32_e32 v23, v23, v24, vcc
	v_cmp_class_f32_e32 vcc, v22, v172
	s_nop 1
	v_cndmask_b32_e32 v24, v23, v22, vcc
	v_div_scale_f32 v25, s[2:3], v24, v24, 1.0
	v_rcp_f32_e32 v26, v25
	v_mad_i64_i32 v[22:23], s[2:3], v152, s51, v[150:151]
	global_store_dwordx4 v[22:23], v[18:21], off
	s_nop 1
	v_fma_f32 v18, -v25, v26, 1.0
	v_fmac_f32_e32 v26, v18, v26
	v_div_scale_f32 v18, vcc, 1.0, v24, 1.0
	v_mul_f32_e32 v19, v18, v26
	v_fma_f32 v20, -v25, v19, v18
	v_fmac_f32_e32 v19, v20, v26
	v_fma_f32 v18, -v25, v19, v18
	v_div_fmas_f32 v18, v18, v26, v19
	v_div_fixup_f32 v18, v18, v24, 1.0
	v_pk_mul_f32 v[14:15], v[14:15], v[18:19] op_sel_hi:[1,0]
	s_andn2_b64 vcc, exec, s[0:1]
	v_mul_f32_e32 v19, 0xbfb8aa3b, v14
	v_exp_f32_e32 v19, v19
	v_mul_f32_e32 v20, 0xbfb8aa3b, v15
	v_exp_f32_e32 v21, v20
	s_mov_b64 s[0:1], -1
	v_pk_mul_f32 v[16:17], v[16:17], v[18:19] op_sel_hi:[1,0]
	v_add_f32_e32 v19, 1.0, v19
	v_rcp_f32_e32 v20, v19
	v_add_f32_e32 v19, 1.0, v21
	v_mul_f32_e32 v21, 0xbfb8aa3b, v16
	v_exp_f32_e32 v22, v21
	v_mul_f32_e32 v21, 0xbfb8aa3b, v17
	v_exp_f32_e32 v23, v21
	v_rcp_f32_e32 v21, v19
	v_add_f32_e32 v19, 1.0, v22
	v_rcp_f32_e32 v22, v19
	v_add_f32_e32 v19, 1.0, v23
	v_pk_mul_f32 v[10:11], v[10:11], v[18:19] op_sel_hi:[1,0]
	v_rcp_f32_e32 v23, v19
	v_pk_mul_f32 v[12:13], v[12:13], v[18:19] op_sel_hi:[1,0]
	v_pk_mul_f32 v[6:7], v[6:7], v[18:19] op_sel_hi:[1,0]
	v_mul_f32_e32 v19, 0xbfb8aa3b, v10
	v_pk_mul_f32 v[14:15], v[14:15], v[20:21]
	v_exp_f32_e32 v19, v19
	v_mul_f32_e32 v20, 0xbfb8aa3b, v11
	v_exp_f32_e32 v21, v20
	v_pk_mul_f32 v[16:17], v[16:17], v[22:23]
	v_pk_mul_f32 v[8:9], v[8:9], v[18:19] op_sel_hi:[1,0]
	v_add_f32_e32 v19, 1.0, v19
	v_rcp_f32_e32 v20, v19
	v_add_f32_e32 v19, 1.0, v21
	v_mul_f32_e32 v21, 0xbfb8aa3b, v12
	v_exp_f32_e32 v22, v21
	v_mul_f32_e32 v21, 0xbfb8aa3b, v13
	v_exp_f32_e32 v23, v21
	v_rcp_f32_e32 v21, v19
	v_add_f32_e32 v19, 1.0, v22
	v_rcp_f32_e32 v22, v19
	v_add_f32_e32 v19, 1.0, v23
	v_rcp_f32_e32 v23, v19
	v_pk_mul_f32 v[6:7], v[6:7], v[14:15]
	v_pk_mul_f32 v[10:11], v[10:11], v[20:21]
	v_pk_mul_f32 v[2:3], v[2:3], v[18:19] op_sel_hi:[1,0]
	v_pk_mul_f32 v[12:13], v[12:13], v[22:23]
	v_pk_mul_f32 v[4:5], v[4:5], v[18:19] op_sel_hi:[1,0]
	v_pk_mul_f32 v[8:9], v[8:9], v[16:17]
	v_pk_mul_f32 v[12:13], v[4:5], v[12:13]
	v_pk_mul_f32 v[4:5], v[2:3], v[10:11]
	v_cvt_pk_bf16_f32 v2, v6, v7
	v_mad_i64_i32 v[6:7], s[2:3], v148, s51, v[150:151]
	v_cvt_pk_bf16_f32 v3, v8, v9
	v_cvt_pk_bf16_f32 v4, v4, v5
	v_cvt_pk_bf16_f32 v5, v12, v13
	global_store_dwordx4 v[6:7], v[2:5], off
	s_cbranch_vccnz .LBB0_1806
	s_andn2_b64 vcc, exec, s[14:15]
	s_cbranch_vccnz .LBB0_1805
	s_barrier
	s_branch .LBB0_1805
